# same as v132 with the two m0-write/LDS-DMA adjacencies separated (m0 write moved above the SALU base add)
# speedup vs baseline: 1.0068x; 1.0068x over previous
.LBB0_280:
	s_waitcnt lgkmcnt(5)
	v_mfma_f32_32x32x16_bf16 v[66:81], v[166:169], v[134:137], v[66:81]
	v_add_f32_e32 v174, v114, v115
	v_add_f32_e32 v175, v116, v117
	v_add_f32_e32 v176, v118, v119
	v_add_f32_e32 v177, v120, v121
	v_add_f32_e32 v174, v174, v122
	s_waitcnt lgkmcnt(4)
	v_mfma_f32_32x32x16_bf16 v[82:97], v[162:165], v[134:137], v[82:97]
	v_add_f32_e32 v175, v175, v123
	v_add_f32_e32 v176, v176, v124
	v_add_f32_e32 v177, v177, v125
	v_add_f32_e32 v174, v174, v126
	v_add_f32_e32 v175, v175, v127
	s_waitcnt lgkmcnt(3)
	v_mfma_f32_32x32x16_bf16 v[66:81], v[158:161], v[138:141], v[66:81]
	v_add_f32_e32 v176, v176, v128
	v_add_f32_e32 v177, v177, v129
	v_add_f32_e32 v174, v174, v98
	v_add_f32_e32 v175, v175, v99
	v_add_f32_e32 v176, v176, v100
	s_waitcnt lgkmcnt(2)
	v_mfma_f32_32x32x16_bf16 v[82:97], v[154:157], v[138:141], v[82:97]
	v_add_f32_e32 v177, v177, v101
	v_add_f32_e32 v174, v174, v102
	v_add_f32_e32 v175, v175, v103
	v_add_f32_e32 v176, v176, v104
	v_add_f32_e32 v177, v177, v105
	s_waitcnt lgkmcnt(1)
	v_mfma_f32_32x32x16_bf16 v[66:81], v[150:153], v[142:145], v[66:81]
	v_add_f32_e32 v174, v174, v106
	v_add_f32_e32 v175, v175, v107
	v_add_f32_e32 v176, v176, v108
	v_add_f32_e32 v177, v177, v109
	s_waitcnt lgkmcnt(0)
	v_mfma_f32_32x32x16_bf16 v[82:97], v[146:149], v[142:145], v[82:97]
	v_add_f32_e32 v174, v174, v110
	v_add_f32_e32 v175, v175, v111
	v_add_f32_e32 v176, v176, v112
	v_add_f32_e32 v177, v177, v113
	v_add_f32_e32 v174, v174, v175
	v_add_f32_e32 v176, v176, v177
	v_cvt_pk_bf16_f32 v113, v112, v113
	v_cvt_pk_bf16_f32 v112, v110, v111
	v_cvt_pk_bf16_f32 v111, v108, v109
	v_cvt_pk_bf16_f32 v110, v106, v107
	v_add_f32_e32 v174, v174, v176
	v_cvt_pk_bf16_f32 v109, v104, v105
	v_cvt_pk_bf16_f32 v108, v102, v103
	v_cvt_pk_bf16_f32 v107, v100, v101
	v_cvt_pk_bf16_f32 v106, v98, v99
	v_cvt_pk_bf16_f32 v98, v114, v115
	v_cvt_pk_bf16_f32 v99, v116, v117
	v_cvt_pk_bf16_f32 v100, v118, v119
	v_cvt_pk_bf16_f32 v101, v120, v121
	v_cvt_pk_bf16_f32 v102, v122, v123
	v_cvt_pk_bf16_f32 v103, v124, v125
	v_cvt_pk_bf16_f32 v104, v126, v127
	v_cvt_pk_bf16_f32 v105, v128, v129
	v_add_f32_e32 v213, v174, v0
	ds_read_b128 v[114:117], v208 offset:49152
	ds_read_b128 v[118:121], v208 offset:53248
	ds_read_b128 v[122:125], v208 offset:57344
	ds_read_b128 v[126:129], v208 offset:61440
	ds_read_b128 v[150:153], v209 offset:53248
	ds_read_b128 v[146:149], v209 offset:49152
	ds_read_b128 v[154:157], v209 offset:57344
	ds_read_b128 v[158:161], v209 offset:61440
	s_and_b32 s0, s77, 0x3f0000
	s_lshl_b32 s22, s0, 1
	s_mov_b32 m0, s73
	s_add_u32 s100, s46, s22
	s_addc_u32 s101, s47, 0
	global_load_lds_dwordx4 v188, s[100:101]
	s_nop 0
	s_mov_b32 m0, s31
	s_lshl_b32 s22, s15, 1
	global_load_lds_dwordx4 v192, s[100:101]
	s_mov_b32 m0, s71
	s_add_u32 s100, s50, s22
	s_addc_u32 s101, s51, 0
	global_load_lds_dwordx4 v190, s[100:101]
	s_nop 0
	s_mov_b32 m0, s72
	s_nop 0
	global_load_lds_dwordx4 v194, s[100:101]
	s_waitcnt lgkmcnt(0)
	v_mfma_f32_32x32x16_bf16 v[50:65], v[98:101], v[114:117], v[50:65]
	ds_read_b128 v[114:117], v210 offset:53248
	v_exp_f32_e32 v66, v66
	v_exp_f32_e32 v67, v67
	v_mfma_f32_32x32x16_bf16 v[34:49], v[98:101], v[118:121], v[34:49]
	ds_read_b128 v[118:121], v210 offset:57344
	v_exp_f32_e32 v68, v68
	v_exp_f32_e32 v69, v69
	v_mfma_f32_32x32x16_bf16 v[18:33], v[98:101], v[122:125], v[18:33]
	ds_read_b128 v[122:125], v210 offset:61440
	v_exp_f32_e32 v70, v70
	v_exp_f32_e32 v71, v71
	v_mfma_f32_32x32x16_bf16 v[2:17], v[98:101], v[126:129], v[2:17]
	ds_read_b128 v[98:101], v210 offset:49152
	v_exp_f32_e32 v72, v72
	v_exp_f32_e32 v73, v73
	v_mfma_f32_32x32x16_bf16 v[50:65], v[102:105], v[146:149], v[50:65]
	ds_read_b128 v[126:129], v212 offset:53248
	v_exp_f32_e32 v74, v74
	v_exp_f32_e32 v75, v75
	v_mfma_f32_32x32x16_bf16 v[34:49], v[102:105], v[150:153], v[34:49]
	ds_read_b128 v[146:149], v212 offset:57344
	v_exp_f32_e32 v76, v76
	v_exp_f32_e32 v77, v77
	v_mfma_f32_32x32x16_bf16 v[18:33], v[102:105], v[154:157], v[18:33]
	ds_read_b128 v[150:153], v212 offset:61440
	v_exp_f32_e32 v78, v78
	v_exp_f32_e32 v79, v79
	v_mfma_f32_32x32x16_bf16 v[2:17], v[102:105], v[158:161], v[2:17]
	ds_read_b128 v[102:105], v212 offset:49152
	v_exp_f32_e32 v80, v80
	v_exp_f32_e32 v81, v81
	s_waitcnt lgkmcnt(0)
	v_mfma_f32_32x32x16_bf16 v[50:65], v[106:109], v[98:101], v[50:65]
	v_exp_f32_e32 v82, v82
	v_exp_f32_e32 v83, v83
	v_mfma_f32_32x32x16_bf16 v[34:49], v[106:109], v[114:117], v[34:49]
	v_exp_f32_e32 v84, v84
	v_exp_f32_e32 v85, v85
	v_mfma_f32_32x32x16_bf16 v[18:33], v[106:109], v[118:121], v[18:33]
	v_exp_f32_e32 v86, v86
	v_exp_f32_e32 v87, v87
	v_mfma_f32_32x32x16_bf16 v[2:17], v[106:109], v[122:125], v[2:17]
	v_exp_f32_e32 v88, v88
	v_exp_f32_e32 v89, v89
	v_mfma_f32_32x32x16_bf16 v[50:65], v[110:113], v[102:105], v[50:65]
	v_exp_f32_e32 v90, v90
	v_exp_f32_e32 v91, v91
	v_mfma_f32_32x32x16_bf16 v[34:49], v[110:113], v[126:129], v[34:49]
	v_exp_f32_e32 v92, v92
	v_exp_f32_e32 v93, v93
	v_mfma_f32_32x32x16_bf16 v[18:33], v[110:113], v[146:149], v[18:33]
	v_exp_f32_e32 v94, v94
	v_exp_f32_e32 v95, v95
	v_mfma_f32_32x32x16_bf16 v[2:17], v[110:113], v[150:153], v[2:17]
	v_exp_f32_e32 v96, v96
	v_exp_f32_e32 v97, v97
	s_waitcnt vmcnt(0)
	s_add_i32 s76, s76, 2
	s_add_i32 s77, s77, 0x20000
	s_cmp_gt_u32 s76, 61
	s_waitcnt vmcnt(0)
	s_barrier
	s_cbranch_scc1 .LBB0_295

.LBB0_288:
	s_waitcnt lgkmcnt(5)
	v_mfma_f32_32x32x16_bf16 v[114:129], v[166:169], v[134:137], v[114:129]
	v_add_f32_e32 v174, v66, v67
	v_add_f32_e32 v175, v68, v69
	v_add_f32_e32 v176, v70, v71
	v_add_f32_e32 v177, v72, v73
	v_add_f32_e32 v174, v174, v74
	s_waitcnt lgkmcnt(4)
	v_mfma_f32_32x32x16_bf16 v[98:113], v[162:165], v[134:137], v[98:113]
	v_add_f32_e32 v175, v175, v75
	v_add_f32_e32 v176, v176, v76
	v_add_f32_e32 v177, v177, v77
	v_add_f32_e32 v174, v174, v78
	v_add_f32_e32 v175, v175, v79
	s_waitcnt lgkmcnt(3)
	v_mfma_f32_32x32x16_bf16 v[114:129], v[158:161], v[138:141], v[114:129]
	v_add_f32_e32 v176, v176, v80
	v_add_f32_e32 v177, v177, v81
	v_add_f32_e32 v174, v174, v82
	v_add_f32_e32 v175, v175, v83
	v_add_f32_e32 v176, v176, v84
	s_waitcnt lgkmcnt(2)
	v_mfma_f32_32x32x16_bf16 v[98:113], v[154:157], v[138:141], v[98:113]
	v_add_f32_e32 v177, v177, v85
	v_add_f32_e32 v174, v174, v86
	v_add_f32_e32 v175, v175, v87
	v_add_f32_e32 v176, v176, v88
	v_add_f32_e32 v177, v177, v89
	s_waitcnt lgkmcnt(1)
	v_mfma_f32_32x32x16_bf16 v[114:129], v[150:153], v[142:145], v[114:129]
	v_add_f32_e32 v174, v174, v90
	v_add_f32_e32 v175, v175, v91
	v_add_f32_e32 v176, v176, v92
	v_add_f32_e32 v177, v177, v93
	s_waitcnt lgkmcnt(0)
	v_mfma_f32_32x32x16_bf16 v[98:113], v[146:149], v[142:145], v[98:113]
	v_add_f32_e32 v174, v174, v94
	v_add_f32_e32 v175, v175, v95
	v_add_f32_e32 v176, v176, v96
	v_add_f32_e32 v177, v177, v97
	v_add_f32_e32 v174, v174, v175
	v_add_f32_e32 v176, v176, v177
	v_cvt_pk_bf16_f32 v66, v66, v67
	v_cvt_pk_bf16_f32 v67, v68, v69
	v_cvt_pk_bf16_f32 v68, v70, v71
	v_cvt_pk_bf16_f32 v69, v72, v73
	v_add_f32_e32 v174, v174, v176
	v_cvt_pk_bf16_f32 v70, v74, v75
	v_cvt_pk_bf16_f32 v71, v76, v77
	v_cvt_pk_bf16_f32 v72, v78, v79
	v_cvt_pk_bf16_f32 v73, v80, v81
	v_cvt_pk_bf16_f32 v74, v82, v83
	v_cvt_pk_bf16_f32 v75, v84, v85
	v_cvt_pk_bf16_f32 v76, v86, v87
	v_cvt_pk_bf16_f32 v77, v88, v89
	v_cvt_pk_bf16_f32 v78, v90, v91
	v_cvt_pk_bf16_f32 v79, v92, v93
	v_cvt_pk_bf16_f32 v80, v94, v95
	v_cvt_pk_bf16_f32 v81, v96, v97
	v_add_f32_e32 v0, v174, v213
	ds_read_b128 v[82:85], v208 offset:32768
	ds_read_b128 v[86:89], v208 offset:36864
	ds_read_b128 v[90:93], v208 offset:40960
	ds_read_b128 v[94:97], v208 offset:45056
	ds_read_b128 v[146:149], v209 offset:32768
	ds_read_b128 v[150:153], v209 offset:36864
	ds_read_b128 v[154:157], v209 offset:40960
	ds_read_b128 v[158:161], v209 offset:45056
	s_add_i32 s14, s77, 0xffff0000
	s_and_b32 s14, s14, 0x3e0000
	s_lshl_b32 s22, s14, 1
	s_mov_b32 m0, s70
	s_add_u32 s100, s46, s22
	s_addc_u32 s101, s47, 0
	global_load_lds_dwordx4 v188, s[100:101]
	s_nop 0
	s_mov_b32 m0, s29
	s_lshl_b32 s22, s80, 1
	global_load_lds_dwordx4 v192, s[100:101]
	s_add_i32 m0, s70, 0xc000
	s_add_u32 s100, s50, s22
	s_addc_u32 s101, s51, 0
	global_load_lds_dwordx4 v190, s[100:101]
	s_nop 0
	s_add_i32 m0, s70, 0xc400
	s_nop 0
	global_load_lds_dwordx4 v194, s[100:101]
	s_waitcnt lgkmcnt(0)
	v_mfma_f32_32x32x16_bf16 v[50:65], v[66:69], v[82:85], v[50:65]
	ds_read_b128 v[82:85], v210 offset:32768
	v_exp_f32_e32 v114, v114
	v_exp_f32_e32 v115, v115
	v_mfma_f32_32x32x16_bf16 v[34:49], v[66:69], v[86:89], v[34:49]
	ds_read_b128 v[86:89], v210 offset:36864
	v_exp_f32_e32 v116, v116
	v_exp_f32_e32 v117, v117
	v_mfma_f32_32x32x16_bf16 v[18:33], v[66:69], v[90:93], v[18:33]
	ds_read_b128 v[90:93], v210 offset:40960
	v_exp_f32_e32 v118, v118
	v_exp_f32_e32 v119, v119
	v_mfma_f32_32x32x16_bf16 v[2:17], v[66:69], v[94:97], v[2:17]
	ds_read_b128 v[66:69], v210 offset:45056
	v_exp_f32_e32 v120, v120
	v_exp_f32_e32 v121, v121
	v_mfma_f32_32x32x16_bf16 v[50:65], v[70:73], v[146:149], v[50:65]
	ds_read_b128 v[94:97], v212 offset:32768
	v_exp_f32_e32 v122, v122
	v_exp_f32_e32 v123, v123
	v_mfma_f32_32x32x16_bf16 v[34:49], v[70:73], v[150:153], v[34:49]
	ds_read_b128 v[146:149], v212 offset:36864
	v_exp_f32_e32 v124, v124
	v_exp_f32_e32 v125, v125
	v_mfma_f32_32x32x16_bf16 v[18:33], v[70:73], v[154:157], v[18:33]
	ds_read_b128 v[150:153], v212 offset:40960
	v_exp_f32_e32 v126, v126
	v_exp_f32_e32 v127, v127
	v_mfma_f32_32x32x16_bf16 v[2:17], v[70:73], v[158:161], v[2:17]
	ds_read_b128 v[70:73], v212 offset:45056
	v_exp_f32_e32 v128, v128
	v_exp_f32_e32 v129, v129
	s_waitcnt lgkmcnt(0)
	v_mfma_f32_32x32x16_bf16 v[50:65], v[74:77], v[82:85], v[50:65]
	v_exp_f32_e32 v98, v98
	v_exp_f32_e32 v99, v99
	v_mfma_f32_32x32x16_bf16 v[34:49], v[74:77], v[86:89], v[34:49]
	v_exp_f32_e32 v100, v100
	v_exp_f32_e32 v101, v101
	v_mfma_f32_32x32x16_bf16 v[18:33], v[74:77], v[90:93], v[18:33]
	v_exp_f32_e32 v102, v102
	v_exp_f32_e32 v103, v103
	v_mfma_f32_32x32x16_bf16 v[2:17], v[74:77], v[66:69], v[2:17]
	v_exp_f32_e32 v104, v104
	v_exp_f32_e32 v105, v105
	v_mfma_f32_32x32x16_bf16 v[50:65], v[78:81], v[94:97], v[50:65]
	v_exp_f32_e32 v106, v106
	v_exp_f32_e32 v107, v107
	v_mfma_f32_32x32x16_bf16 v[34:49], v[78:81], v[146:149], v[34:49]
	v_exp_f32_e32 v108, v108
	v_exp_f32_e32 v109, v109
	v_mfma_f32_32x32x16_bf16 v[18:33], v[78:81], v[150:153], v[18:33]
	v_exp_f32_e32 v110, v110
	v_exp_f32_e32 v111, v111
	v_mfma_f32_32x32x16_bf16 v[2:17], v[78:81], v[70:73], v[2:17]
	v_exp_f32_e32 v112, v112
	v_exp_f32_e32 v113, v113
	s_and_b64 s[0:1], s[0:1], exec
	s_waitcnt vmcnt(0)
	s_cselect_b32 s14, 1, 2
	s_and_b64 s[0:1], s[40:41], exec
	s_cselect_b32 s14, s14, 0
	s_cmp_eq_u32 s14, s79
	s_waitcnt vmcnt(0)
	s_barrier
	s_cbranch_scc1 .LBB0_290
	s_cmp_eq_u32 s79, 0
	s_cselect_b64 vcc, -1, 0
	s_cmp_eq_u32 s79, 2
	s_cselect_b64 s[0:1], -1, 0
	v_cndmask_b32_e64 v66, 0, v201, s[0:1]
	s_cmp_eq_u32 s14, 2
	v_cndmask_b32_e32 v66, v66, v200, vcc
	s_cselect_b64 vcc, -1, 0
	v_cndmask_b32_e32 v67, 0, v201, vcc
	v_cndmask_b32_e64 v67, v200, v67, s[40:41]
	v_sub_f32_e32 v66, v66, v67
	v_exp_f32_e32 v66, v66
	s_nop 0
	v_pk_mul_f32 v[64:65], v[66:67], v[64:65] op_sel_hi:[0,1]
	v_pk_mul_f32 v[62:63], v[66:67], v[62:63] op_sel_hi:[0,1]
	v_pk_mul_f32 v[60:61], v[66:67], v[60:61] op_sel_hi:[0,1]
	v_pk_mul_f32 v[58:59], v[66:67], v[58:59] op_sel_hi:[0,1]
	v_pk_mul_f32 v[56:57], v[66:67], v[56:57] op_sel_hi:[0,1]
	v_pk_mul_f32 v[54:55], v[66:67], v[54:55] op_sel_hi:[0,1]
	v_pk_mul_f32 v[52:53], v[66:67], v[52:53] op_sel_hi:[0,1]
	v_pk_mul_f32 v[50:51], v[66:67], v[50:51] op_sel_hi:[0,1]
	v_pk_mul_f32 v[48:49], v[66:67], v[48:49] op_sel_hi:[0,1]
	v_pk_mul_f32 v[46:47], v[66:67], v[46:47] op_sel_hi:[0,1]
	v_pk_mul_f32 v[44:45], v[66:67], v[44:45] op_sel_hi:[0,1]
	v_pk_mul_f32 v[42:43], v[66:67], v[42:43] op_sel_hi:[0,1]
	v_pk_mul_f32 v[40:41], v[66:67], v[40:41] op_sel_hi:[0,1]
	v_pk_mul_f32 v[38:39], v[66:67], v[38:39] op_sel_hi:[0,1]
	v_pk_mul_f32 v[36:37], v[66:67], v[36:37] op_sel_hi:[0,1]
	v_pk_mul_f32 v[34:35], v[66:67], v[34:35] op_sel_hi:[0,1]
	v_pk_mul_f32 v[32:33], v[66:67], v[32:33] op_sel_hi:[0,1]
	v_pk_mul_f32 v[30:31], v[66:67], v[30:31] op_sel_hi:[0,1]
	v_pk_mul_f32 v[28:29], v[66:67], v[28:29] op_sel_hi:[0,1]
	v_pk_mul_f32 v[26:27], v[66:67], v[26:27] op_sel_hi:[0,1]
	v_pk_mul_f32 v[24:25], v[66:67], v[24:25] op_sel_hi:[0,1]
	v_pk_mul_f32 v[22:23], v[66:67], v[22:23] op_sel_hi:[0,1]
	v_pk_mul_f32 v[20:21], v[66:67], v[20:21] op_sel_hi:[0,1]
	v_pk_mul_f32 v[18:19], v[66:67], v[18:19] op_sel_hi:[0,1]
	v_pk_mul_f32 v[16:17], v[66:67], v[16:17] op_sel_hi:[0,1]
	v_pk_mul_f32 v[14:15], v[66:67], v[14:15] op_sel_hi:[0,1]
	v_pk_mul_f32 v[12:13], v[66:67], v[12:13] op_sel_hi:[0,1]
	v_pk_mul_f32 v[10:11], v[66:67], v[10:11] op_sel_hi:[0,1]
	v_pk_mul_f32 v[8:9], v[66:67], v[8:9] op_sel_hi:[0,1]
	v_pk_mul_f32 v[6:7], v[66:67], v[6:7] op_sel_hi:[0,1]
	v_pk_mul_f32 v[4:5], v[66:67], v[4:5] op_sel_hi:[0,1]
	v_pk_mul_f32 v[2:3], v[66:67], v[2:3] op_sel_hi:[0,1]
	v_mul_f32_e32 v0, v0, v66
	s_branch .LBB0_291
